# S12 with sc1 (L1 bypass) on the attention loop's K/V LDS-DMA loads
# speedup vs baseline: 1.0017x; 1.0017x over previous
; #define SBAR() __builtin_amdgcn_sched_barrier(0)
; __device__ __forceinline__ void finishSM(f32x16& p0, f32x16& p1, float alpha, float& l_reg, bf16x8& pa0, bf16x8& pa1, bf16x8& pa2, bf16x8& pa3) {
;   for (int r = 0; r < 16; ++r) p1[r] = __builtin_amdgcn_exp2f(p1[r]);
;   float ps = 0; for (int r = 0; r < 16; ++r) ps += p0[r]; for (int r = 0; r < 16; ++r) ps += p1[r];
;   { auto rr = __builtin_amdgcn_permlane32_swap(__float_as_uint(ps), __float_as_uint(ps), false, false);
;     ps = __uint_as_float(rr[0]) + __uint_as_float(rr[1]); }
;   l_reg = l_reg * alpha + ps;
;     ...
;   PK4(p0, 0, pa0); PK4(p0, 8, pa1); PK4(p1, 0, pa2); PK4(p1, 8, pa3);
;     ...
; }
; __device__ __forceinline__ void kload(bf16x8 (&kf)[8], const char* Ks, int r32, int hi, int sb) {
; #pragma unroll
;   for (int d0 = 0; d0 < 4; ++d0) { const int cb = sb + (d0 * 16 + hi * 8) * 2;
;     kf[2 * d0] = *reinterpret_cast<const bf16x8*>(Ks + KSWZ(r32, cb)); kf[2 * d0 + 1] = *reinterpret_cast<const bf16x8*>(Ks + KSWZ(32 + r32, cb)); }
; }
; __device__ __forceinline__ void kmma(f32x16& p0, f32x16& p1, const bf16x8 (&kf)[8], const bf16x8* qr) {
;   asm volatile("s_waitcnt lgkmcnt(0)" ::: "memory"); SBAR();
;   p0 = f32x16{}; p1 = f32x16{};
; #pragma unroll
;   for (int d0 = 0; d0 < 4; ++d0) { p0 = __builtin_amdgcn_mfma_f32_32x32x16_bf16(kf[2 * d0], qr[d0], p0, 0, 0, 0); p1 = __builtin_amdgcn_mfma_f32_32x32x16_bf16(kf[2 * d0 + 1], qr[d0], p1, 0, 0, 0); }
; }
.LBB0_770:
	ds_read_b128 v[82:85], v245
	ds_read_b128 v[86:89], v245 offset:8192
	ds_read_b128 v[130:133], v246
	ds_read_b128 v[134:137], v246 offset:8192
	ds_read_b128 v[206:209], v247
	ds_read_b128 v[210:213], v247 offset:8192
	ds_read_b128 v[214:217], v255
	ds_read_b128 v[218:221], v255 offset:8192
	v_exp_f32_e32 v148, v66
	v_add_f32_e32 v66, 0, v175
	v_add_f32_e32 v66, v177, v66
	v_add_f32_e32 v66, v192, v66
	v_add_f32_e32 v66, v195, v66
	v_add_f32_e32 v66, v196, v66
	v_add_f32_e32 v66, v199, v66
	v_add_f32_e32 v66, v200, v66
	v_add_f32_e32 v66, v203, v66
	v_add_f32_e32 v66, v176, v66
	v_add_f32_e32 v66, v193, v66
	v_add_f32_e32 v66, v194, v66
	v_add_f32_e32 v66, v197, v66
	v_add_f32_e32 v66, v198, v66
	v_exp_f32_e32 v149, v67
	v_add_f32_e32 v66, v201, v66
	s_waitcnt lgkmcnt(7)
	v_mfma_f32_32x32x16_bf16 v[98:113], v[82:85], v[126:129], 0
	v_exp_f32_e32 v150, v68
	s_and_b32 s13, s36, 0xc000
	v_add_f32_e32 v66, v202, v66
	v_add_u32_e32 v244, s13, v164
	v_exp_f32_e32 v151, v69
	ds_read_b64_tr_b16 v[228:229], v244 offset:0
	v_add_f32_e32 v66, v204, v66
	ds_read_b64_tr_b16 v[230:231], v244 offset:0x800
	ds_read_b64_tr_b16 v[232:233], v244 offset:0x1000
	ds_read_b64_tr_b16 v[234:235], v244 offset:0x1800
	s_waitcnt lgkmcnt(10)
	v_mfma_f32_32x32x16_bf16 v[82:97], v[86:89], v[126:129], 0
	v_exp_f32_e32 v186, v70
	ds_read_b64_tr_b16 v[236:237], v244 offset:0x2000
	v_add_f32_e32 v66, v148, v66
	ds_read_b64_tr_b16 v[238:239], v244 offset:0x2800
	v_exp_f32_e32 v187, v71
	ds_read_b64_tr_b16 v[240:241], v244 offset:0x3000
	v_add_f32_e32 v66, v149, v66
	ds_read_b64_tr_b16 v[242:243], v244 offset:0x3800
	v_exp_f32_e32 v188, v72
	s_add_i32 s37, s12, 2
	s_cmpk_lt_u32 s12, 0x7e
	s_cselect_b64 s[0:1], -1, 0
	s_waitcnt lgkmcnt(13)
	v_mfma_f32_32x32x16_bf16 v[98:113], v[130:133], v[122:125], v[98:113]
	v_add_f32_e32 v66, v150, v66
	s_and_b64 s[10:11], s[0:1], exec
	v_exp_f32_e32 v189, v73
	s_cselect_b32 s10, 0, 0xffffff80
	v_add_f32_e32 v66, v151, v66
	s_add_i32 s58, s37, s10
	v_exp_f32_e32 v205, v74
	s_and_b64 s[0:1], s[0:1], exec
	s_cselect_b32 s1, s9, s30
	s_cselect_b32 s0, s8, s26
	s_lshl_b64 s[10:11], s[58:59], 17
	s_waitcnt lgkmcnt(12)
	v_mfma_f32_32x32x16_bf16 v[82:97], v[134:137], v[122:125], v[82:97]
	v_add_f32_e32 v66, v186, v66
	s_lshl_b64 s[0:1], s[0:1], 11
	v_exp_f32_e32 v222, v75
	s_add_u32 s10, s10, s0
	v_add_f32_e32 v66, v187, v66
	s_addc_u32 s11, s11, s1
	v_exp_f32_e32 v223, v76
	s_add_u32 s0, s20, s10
	v_add_f32_e32 v66, v188, v66
	s_addc_u32 s1, s21, s11
	s_add_u32 s10, s22, s10
	s_addc_u32 s11, s23, s11
	s_waitcnt lgkmcnt(11)
	v_mfma_f32_32x32x16_bf16 v[98:113], v[206:209], v[118:121], v[98:113]
	v_exp_f32_e32 v224, v77
	s_and_b32 s13, s37, 0xff
	v_add_f32_e32 v66, v189, v66
	s_mulk_i32 s13, 0xab
	v_exp_f32_e32 v225, v78
	s_lshr_b32 s13, s13, 9
	v_add_f32_e32 v66, v205, v66
	s_mul_i32 s13, s13, 3
	s_sub_i32 s13, s37, s13
	s_and_b32 s13, s13, 0xff
	s_waitcnt lgkmcnt(10)
	v_mfma_f32_32x32x16_bf16 v[82:97], v[210:213], v[118:121], v[82:97]
	v_exp_f32_e32 v226, v79
	s_lshl_b32 s13, s13, 14
	s_mov_b32 s100, s13
	v_add_f32_e32 v66, v222, v66
	s_add_i32 s42, s36, 0xffffc000
	v_exp_f32_e32 v227, v80
	s_and_b32 s42, s42, 0xc000
	v_add_f32_e32 v66, v223, v66
	s_add_i32 s13, s13, s27
	v_exp_f32_e32 v81, v81
	s_add_i32 s42, s42, s31
	v_lshl_add_u64 v[246:247], s[0:1], 0, v[146:147]
	s_mov_b32 m0, s13
	s_waitcnt lgkmcnt(9)
	v_mfma_f32_32x32x16_bf16 v[98:113], v[214:217], v[114:117], v[98:113]
	v_add_f32_e32 v66, v224, v66
	s_nop 0
	v_add_f32_e32 v66, v225, v66
	global_load_lds_dwordx4 v[246:247], off sc1
	v_add_f32_e32 v66, v226, v66
	v_lshl_add_u64 v[246:247], s[10:11], 0, v[142:143]
	v_add_f32_e32 v66, v227, v66
	s_mov_b32 m0, s42
	s_nop 0
	global_load_lds_dwordx4 v[246:247], off sc1
	v_lshl_add_u64 v[246:247], s[0:1], 0, v[144:145]
	s_waitcnt lgkmcnt(8)
	v_mfma_f32_32x32x16_bf16 v[82:97], v[218:221], v[114:117], v[82:97]
	v_add_f32_e32 v130, v81, v66
	s_add_i32 m0, s13, 0x2000
	v_mov_b32_e32 v131, v130
	s_nop 0
	v_cvt_pk_bf16_f32 v66, v175, v177
	global_load_lds_dwordx4 v[246:247], off sc1
	v_cvt_pk_bf16_f32 v67, v192, v195
	v_lshl_add_u64 v[246:247], s[10:11], 0, v[154:155]
	v_cvt_pk_bf16_f32 v68, v196, v199
	s_add_i32 m0, s42, 0x2000
	s_nop 0
	global_load_lds_dwordx4 v[246:247], off sc1
	v_permlane32_swap_b32_e32 v130, v131
	v_cvt_pk_bf16_f32 v69, v200, v203
	v_permlane32_swap_b32_e32 v66, v68
	v_cvt_pk_bf16_f32 v70, v176, v193
	v_cvt_pk_bf16_f32 v71, v194, v197
	v_cvt_pk_bf16_f32 v72, v198, v201
	v_cvt_pk_bf16_f32 v73, v202, v204
	v_cvt_pk_bf16_f32 v74, v148, v149
	v_cvt_pk_bf16_f32 v75, v150, v151
	v_cvt_pk_bf16_f32 v76, v186, v187
	v_cvt_pk_bf16_f32 v77, v188, v189
	v_cvt_pk_bf16_f32 v78, v205, v222
	v_cvt_pk_bf16_f32 v79, v223, v224
	v_cvt_pk_bf16_f32 v80, v225, v226
	v_cvt_pk_bf16_f32 v81, v227, v81
	v_permlane32_swap_b32_e32 v67, v69
	v_permlane32_swap_b32_e32 v70, v72
	v_permlane32_swap_b32_e32 v71, v73
	v_permlane32_swap_b32_e32 v74, v76
	v_permlane32_swap_b32_e32 v75, v77
	v_permlane32_swap_b32_e32 v78, v80
	v_permlane32_swap_b32_e32 v79, v81
	ds_read_b64_tr_b16 v[204:205], v244 offset:0x200
	ds_read_b64_tr_b16 v[206:207], v244 offset:0xa00
	ds_read_b64_tr_b16 v[208:209], v244 offset:0x1200
	ds_read_b64_tr_b16 v[210:211], v244 offset:0x1a00
	ds_read_b64_tr_b16 v[212:213], v244 offset:0x2200
	ds_read_b64_tr_b16 v[214:215], v244 offset:0x2a00
	ds_read_b64_tr_b16 v[216:217], v244 offset:0x3200
	ds_read_b64_tr_b16 v[218:219], v244 offset:0x3a00
	s_waitcnt lgkmcnt(14)
; #define SBAR() __builtin_amdgcn_sched_barrier(0)
; __device__ __forceinline__ void partialSM(f32x16& p0, f32x16& p1, float& m_reg, float& mn, float& alpha) {
;   constexpr float C = SCALE * 1.4426950408889634f;
;   float pmax = p0[0]; for (int r = 1; r < 16; ++r) pmax = fmaxf(pmax, p0[r]); for (int r = 0; r < 16; ++r) pmax = fmaxf(pmax, p1[r]);
;   { auto rr = __builtin_amdgcn_permlane32_swap(__float_as_uint(pmax), __float_as_uint(pmax), false, false);
;     pmax = fmaxf(__uint_as_float(rr[0]), __uint_as_float(rr[1])); }
;   if (__builtin_expect(__all(pmax - m_reg <= THR / SCALE), 1)) { mn = m_reg; alpha = 1.f; }
;   else { mn = fmaxf(m_reg, pmax); alpha = __builtin_amdgcn_exp2f((m_reg - mn) * C); m_reg = mn; }
;   float mnC = -mn * C;
;   for (int r = 0; r < 16; ++r) p0[r] = fmaf(p0[r], C, mnC); for (int r = 0; r < 16; ++r) p1[r] = fmaf(p1[r], C, mnC);
;   for (int r = 0; r < 16; ++r) p0[r] = __builtin_amdgcn_exp2f(p0[r]);
; }
; __device__ __forceinline__ void pv_d0(f32x16* o, int vb, bf16x8 pa0, bf16x8 pa1, bf16x8 pa2, bf16x8 pa3) {
;   VFrag fa, fb;
;   v_frag_read<0>(fa, vb);
;   asm volatile("s_waitcnt lgkmcnt(0)" ::: "memory"); SBAR();
;   v_frag_read<1>(fb, vb); SBAR();
;   pv_mma(o[0], fa, pa0, pa1, pa2, pa3); SBAR();
;   asm volatile("s_waitcnt lgkmcnt(0)" ::: "memory"); SBAR();
;   v_frag_read<2>(fa, vb); SBAR();
;   pv_mma(o[1], fb, pa0, pa1, pa2, pa3); SBAR();
;   asm volatile("s_waitcnt lgkmcnt(0)" ::: "memory"); SBAR();
;   v_frag_read<3>(fb, vb); SBAR();
;   pv_mma(o[2], fa, pa0, pa1, pa2, pa3); SBAR();
;   asm volatile("s_waitcnt lgkmcnt(0)" ::: "memory"); SBAR();
;   pv_mma(o[3], fb, pa0, pa1, pa2, pa3);
; }
	v_mfma_f32_32x32x16_bf16 v[18:33], v[66:69], v[228:231], v[18:33]
	v_max_f32_e32 v245, v99, v99
	v_max_f32_e32 v246, v98, v98
	v_max_f32_e32 v245, v246, v245
	v_max3_f32 v245, v245, v100, v101
	v_max3_f32 v245, v245, v102, v103
	v_max3_f32 v245, v245, v104, v105
	v_max3_f32 v245, v245, v106, v107
	v_max3_f32 v245, v245, v108, v109
	s_waitcnt lgkmcnt(12)
	v_mfma_f32_32x32x16_bf16 v[18:33], v[70:73], v[232:235], v[18:33]
	v_max3_f32 v245, v245, v110, v111
	v_max3_f32 v245, v245, v112, v113
	v_max3_f32 v245, v245, v82, v83
	v_max3_f32 v245, v245, v84, v85
	v_max3_f32 v245, v245, v86, v87
	v_max3_f32 v245, v245, v88, v89
	v_max3_f32 v245, v245, v90, v91
	v_max3_f32 v245, v245, v92, v93
	s_waitcnt lgkmcnt(10)
	v_mfma_f32_32x32x16_bf16 v[18:33], v[74:77], v[236:239], v[18:33]
	v_max3_f32 v245, v245, v94, v95
	v_max3_f32 v245, v245, v96, v97
	v_mov_b32_e32 v246, v245
	s_nop 1
	v_permlane32_swap_b32_e32 v245, v246
	v_max_f32_e32 v246, v246, v246
	v_max_f32_e32 v245, v245, v245
	v_max_f32_e32 v245, v245, v246
	v_sub_f32_e32 v246, v245, v174
	s_waitcnt lgkmcnt(8)
	v_mfma_f32_32x32x16_bf16 v[18:33], v[78:81], v[240:243], v[18:33]
	v_cmp_ge_f32_e32 vcc, s63, v246
	v_max_f32_e32 v246, v174, v174
	v_max_f32_e32 v245, v246, v245
	v_sub_f32_e32 v246, v174, v245
	v_mul_f32_e32 v246, 0x3e38aa3b, v246
	v_exp_f32_e32 v246, v246
	s_cmp_eq_u64 vcc, exec
	s_cselect_b64 s[0:1], -1, 0
	v_cndmask_b32_e64 v132, v246, 1.0, s[0:1]
	ds_read_b64_tr_b16 v[228:229], v244 offset:0x400
	ds_read_b64_tr_b16 v[230:231], v244 offset:0xc00
	ds_read_b64_tr_b16 v[232:233], v244 offset:0x1400
	ds_read_b64_tr_b16 v[234:235], v244 offset:0x1c00
	ds_read_b64_tr_b16 v[236:237], v244 offset:0x2400
	ds_read_b64_tr_b16 v[238:239], v244 offset:0x2c00
	ds_read_b64_tr_b16 v[240:241], v244 offset:0x3400
	ds_read_b64_tr_b16 v[242:243], v244 offset:0x3c00
	v_cndmask_b32_e64 v133, v245, v174, s[0:1]
	v_mul_f32_e32 v148, 0xbe38aa3b, v133
	s_waitcnt lgkmcnt(14)
	v_mfma_f32_32x32x16_bf16 v[50:65], v[66:69], v[204:207], v[50:65]
	v_fmamk_f32 v98, v98, 0x3e38aa3b, v148
	v_fmamk_f32 v99, v99, 0x3e38aa3b, v148
	v_fmamk_f32 v100, v100, 0x3e38aa3b, v148
	v_fmamk_f32 v101, v101, 0x3e38aa3b, v148
	s_waitcnt lgkmcnt(12)
	v_mfma_f32_32x32x16_bf16 v[50:65], v[70:73], v[208:211], v[50:65]
	v_fmamk_f32 v102, v102, 0x3e38aa3b, v148
	v_fmamk_f32 v103, v103, 0x3e38aa3b, v148
	v_fmamk_f32 v104, v104, 0x3e38aa3b, v148
	v_fmamk_f32 v105, v105, 0x3e38aa3b, v148
	s_waitcnt lgkmcnt(10)
	v_mfma_f32_32x32x16_bf16 v[50:65], v[74:77], v[212:215], v[50:65]
	v_fmamk_f32 v106, v106, 0x3e38aa3b, v148
	v_fmamk_f32 v107, v107, 0x3e38aa3b, v148
	v_fmamk_f32 v108, v108, 0x3e38aa3b, v148
	v_fmamk_f32 v109, v109, 0x3e38aa3b, v148
	s_waitcnt lgkmcnt(8)
	v_mfma_f32_32x32x16_bf16 v[50:65], v[78:81], v[216:219], v[50:65]
	v_fmamk_f32 v110, v110, 0x3e38aa3b, v148
	v_fmamk_f32 v111, v111, 0x3e38aa3b, v148
	v_fmamk_f32 v112, v112, 0x3e38aa3b, v148
	v_fmamk_f32 v113, v113, 0x3e38aa3b, v148
	ds_read_b64_tr_b16 v[204:205], v244 offset:0x600
	ds_read_b64_tr_b16 v[206:207], v244 offset:0xe00
	ds_read_b64_tr_b16 v[208:209], v244 offset:0x1600
	ds_read_b64_tr_b16 v[210:211], v244 offset:0x1e00
	ds_read_b64_tr_b16 v[212:213], v244 offset:0x2600
	ds_read_b64_tr_b16 v[214:215], v244 offset:0x2e00
	ds_read_b64_tr_b16 v[216:217], v244 offset:0x3600
	ds_read_b64_tr_b16 v[218:219], v244 offset:0x3e00
	s_waitcnt lgkmcnt(14)
	v_mfma_f32_32x32x16_bf16 v[34:49], v[66:69], v[228:231], v[34:49]
	v_fmamk_f32 v82, v82, 0x3e38aa3b, v148
	v_fmamk_f32 v83, v83, 0x3e38aa3b, v148
	v_fmamk_f32 v84, v84, 0x3e38aa3b, v148
	v_fmamk_f32 v85, v85, 0x3e38aa3b, v148
	s_waitcnt lgkmcnt(12)
	v_mfma_f32_32x32x16_bf16 v[34:49], v[70:73], v[232:235], v[34:49]
	v_fmamk_f32 v86, v86, 0x3e38aa3b, v148
	v_fmamk_f32 v87, v87, 0x3e38aa3b, v148
	s_add_i32 s13, s36, 0xffff4000
	v_fmamk_f32 v149, v88, 0x3e38aa3b, v148
	s_waitcnt lgkmcnt(10)
	v_mfma_f32_32x32x16_bf16 v[34:49], v[74:77], v[236:239], v[34:49]
	v_fmamk_f32 v150, v89, 0x3e38aa3b, v148
	v_fmamk_f32 v151, v90, 0x3e38aa3b, v148
	v_fmamk_f32 v186, v91, 0x3e38aa3b, v148
	v_fmamk_f32 v187, v92, 0x3e38aa3b, v148
	s_waitcnt lgkmcnt(8)
	v_mfma_f32_32x32x16_bf16 v[34:49], v[78:81], v[240:243], v[34:49]
	v_fmamk_f32 v188, v93, 0x3e38aa3b, v148
	v_fmamk_f32 v189, v94, 0x3e38aa3b, v148
	v_exp_f32_e32 v192, v98
	v_exp_f32_e32 v193, v99
	v_exp_f32_e32 v194, v100
	v_exp_f32_e32 v195, v101
	s_waitcnt lgkmcnt(6)
	v_mfma_f32_32x32x16_bf16 v[2:17], v[66:69], v[204:207], v[2:17]
	v_exp_f32_e32 v196, v102
	v_exp_f32_e32 v197, v103
	v_exp_f32_e32 v198, v104
	v_exp_f32_e32 v199, v105
	s_waitcnt lgkmcnt(4)
	v_mfma_f32_32x32x16_bf16 v[2:17], v[70:73], v[208:211], v[2:17]
	v_exp_f32_e32 v200, v106
	v_exp_f32_e32 v201, v107
	v_exp_f32_e32 v202, v108
	v_exp_f32_e32 v203, v109
	v_exp_f32_e32 v204, v110
	v_exp_f32_e32 v205, v111
	s_waitcnt lgkmcnt(2)
	v_mfma_f32_32x32x16_bf16 v[2:17], v[74:77], v[212:215], v[2:17]
	v_exp_f32_e32 v206, v112
	v_exp_f32_e32 v207, v113
	v_fmamk_f32 v208, v95, 0x3e38aa3b, v148
	v_fmamk_f32 v209, v96, 0x3e38aa3b, v148
	v_fmac_f32_e32 v148, 0x3e38aa3b, v97
	s_waitcnt lgkmcnt(0)
	v_mfma_f32_32x32x16_bf16 v[2:17], v[78:81], v[216:219], v[2:17]
	v_add_u32_e32 v245, s101, v169
	v_add_u32_e32 v246, s101, v170
	v_add_u32_e32 v247, s101, v171
	v_add_u32_e32 v255, s101, v172
	v_cmp_gt_f32_e32 vcc, 1.0, v132
	s_cbranch_vccz .LBB0_774
	s_and_saveexec_b64 s[10:11], s[40:41]
	ds_write_b32 v162, v132 offset:128
	s_or_b64 exec, exec, s[10:11]
	s_waitcnt lgkmcnt(0)
	v_add_u32_e32 v67, s18, v140
	ds_read_b128 v[68:71], v67 offset:224
	ds_read_b128 v[72:75], v67 offset:192
	ds_read_b128 v[76:79], v67 offset:160
	ds_read_b128 v[134:137], v67 offset:128
	s_waitcnt lgkmcnt(0)
	v_pk_mul_f32 v[30:31], v[30:31], v[68:69]
	v_pk_mul_f32 v[26:27], v[26:27], v[72:73]
	v_pk_mul_f32 v[22:23], v[22:23], v[76:77]
	v_pk_mul_f32 v[32:33], v[32:33], v[70:71]
	v_pk_mul_f32 v[28:29], v[28:29], v[74:75]
	v_pk_mul_f32 v[24:25], v[24:25], v[78:79]
	v_pk_mul_f32 v[20:21], v[20:21], v[136:137]
	v_pk_mul_f32 v[18:19], v[18:19], v[134:135]
	v_pk_mul_f32 v[62:63], v[62:63], v[68:69]
	v_pk_mul_f32 v[58:59], v[58:59], v[72:73]
	v_pk_mul_f32 v[54:55], v[54:55], v[76:77]
	v_pk_mul_f32 v[64:65], v[64:65], v[70:71]
	v_pk_mul_f32 v[60:61], v[60:61], v[74:75]
	v_pk_mul_f32 v[56:57], v[56:57], v[78:79]
	v_pk_mul_f32 v[52:53], v[52:53], v[136:137]
	v_pk_mul_f32 v[50:51], v[50:51], v[134:135]
	v_pk_mul_f32 v[46:47], v[46:47], v[68:69]
	v_pk_mul_f32 v[42:43], v[42:43], v[72:73]
	v_pk_mul_f32 v[38:39], v[38:39], v[76:77]
	v_pk_mul_f32 v[48:49], v[48:49], v[70:71]
	v_pk_mul_f32 v[44:45], v[44:45], v[74:75]
	v_pk_mul_f32 v[40:41], v[40:41], v[78:79]
	v_pk_mul_f32 v[36:37], v[36:37], v[136:137]
	v_pk_mul_f32 v[34:35], v[34:35], v[134:135]
	v_pk_mul_f32 v[14:15], v[14:15], v[68:69]
	v_pk_mul_f32 v[10:11], v[10:11], v[72:73]
	v_pk_mul_f32 v[6:7], v[6:7], v[76:77]
	v_pk_mul_f32 v[16:17], v[16:17], v[70:71]
	v_pk_mul_f32 v[12:13], v[12:13], v[74:75]
	v_pk_mul_f32 v[8:9], v[8:9], v[78:79]
	v_pk_mul_f32 v[4:5], v[4:5], v[136:137]
	v_pk_mul_f32 v[2:3], v[2:3], v[134:135]
; #define SBAR() __builtin_amdgcn_sched_barrier(0)
; __device__ __forceinline__ void finishSM(f32x16& p0, f32x16& p1, float alpha, float& l_reg, bf16x8& pa0, bf16x8& pa1, bf16x8& pa2, bf16x8& pa3) {
;   for (int r = 0; r < 16; ++r) p1[r] = __builtin_amdgcn_exp2f(p1[r]);
;   float ps = 0; for (int r = 0; r < 16; ++r) ps += p0[r]; for (int r = 0; r < 16; ++r) ps += p1[r];
;   { auto rr = __builtin_amdgcn_permlane32_swap(__float_as_uint(ps), __float_as_uint(ps), false, false);
;     ps = __uint_as_float(rr[0]) + __uint_as_float(rr[1]); }
;   l_reg = l_reg * alpha + ps;
;     ...
;   PK4(p0, 0, pa0); PK4(p0, 8, pa1); PK4(p1, 0, pa2); PK4(p1, 8, pa3);
;     ...
; }
; __device__ __forceinline__ void kload(bf16x8 (&kf)[8], const char* Ks, int r32, int hi, int sb) {
; #pragma unroll
;   for (int d0 = 0; d0 < 4; ++d0) { const int cb = sb + (d0 * 16 + hi * 8) * 2;
;     kf[2 * d0] = *reinterpret_cast<const bf16x8*>(Ks + KSWZ(r32, cb)); kf[2 * d0 + 1] = *reinterpret_cast<const bf16x8*>(Ks + KSWZ(32 + r32, cb)); }
; }
; __device__ __forceinline__ void kmma(f32x16& p0, f32x16& p1, const bf16x8 (&kf)[8], const bf16x8* qr) {
;   asm volatile("s_waitcnt lgkmcnt(0)" ::: "memory"); SBAR();
;   p0 = f32x16{}; p1 = f32x16{};
; #pragma unroll
;   for (int d0 = 0; d0 < 4; ++d0) { p0 = __builtin_amdgcn_mfma_f32_32x32x16_bf16(kf[2 * d0], qr[d0], p0, 0, 0, 0); p1 = __builtin_amdgcn_mfma_f32_32x32x16_bf16(kf[2 * d0 + 1], qr[d0], p1, 0, 0, 0); }
; }
; __device__ __forceinline__ void qkt(f32x16& p0, f32x16& p1, const char* Ks, const bf16x8* qr, int r32, int hi, int sb) {
;   bf16x8 kf[8]; kload(kf, Ks, r32, hi, sb); SBAR(); kmma(p0, p1, kf, qr);
.LBB0_774:
	s_waitcnt vmcnt(4)
	s_barrier
	ds_read_b128 v[66:69], v245
	ds_read_b128 v[70:73], v245 offset:8192
	ds_read_b128 v[98:101], v246
	ds_read_b128 v[102:105], v246 offset:8192
	ds_read_b128 v[106:109], v247
	ds_read_b128 v[110:113], v247 offset:8192
	ds_read_b128 v[134:137], v255
	ds_read_b128 v[174:177], v255 offset:8192
	v_exp_f32_e32 v210, v82
	v_exp_f32_e32 v211, v83
	v_exp_f32_e32 v212, v84
	v_exp_f32_e32 v213, v85
	v_exp_f32_e32 v214, v86
	v_exp_f32_e32 v215, v87
	v_add_f32_e32 v216, 0, v192
	v_add_f32_e32 v216, v193, v216
	v_add_f32_e32 v216, v194, v216
	v_add_f32_e32 v216, v195, v216
	v_exp_f32_e32 v149, v149
	v_exp_f32_e32 v150, v150
	v_exp_f32_e32 v151, v151
	v_exp_f32_e32 v186, v186
	v_exp_f32_e32 v187, v187
	v_exp_f32_e32 v188, v188
	s_waitcnt lgkmcnt(7)
	v_mfma_f32_32x32x16_bf16 v[82:97], v[66:69], v[126:129], 0
	v_exp_f32_e32 v189, v189
	s_and_b32 s46, s13, 0xc000
	v_exp_f32_e32 v208, v208
	v_add_u32_e32 v244, s46, v164
	v_exp_f32_e32 v209, v209
	ds_read_b64_tr_b16 v[228:229], v244 offset:0
	v_exp_f32_e32 v148, v148
	ds_read_b64_tr_b16 v[230:231], v244 offset:0x800
	ds_read_b64_tr_b16 v[232:233], v244 offset:0x1000
	s_waitcnt lgkmcnt(9)
	v_mfma_f32_32x32x16_bf16 v[66:81], v[70:73], v[126:129], 0
	v_add_f32_e32 v255, v196, v216
	ds_read_b64_tr_b16 v[234:235], v244 offset:0x1800
	v_add_f32_e32 v255, v197, v255
	ds_read_b64_tr_b16 v[236:237], v244 offset:0x2000
	v_add_f32_e32 v255, v198, v255
	ds_read_b64_tr_b16 v[238:239], v244 offset:0x2800
	v_add_f32_e32 v255, v199, v255
	ds_read_b64_tr_b16 v[240:241], v244 offset:0x3000
	v_add_f32_e32 v255, v200, v255
	ds_read_b64_tr_b16 v[242:243], v244 offset:0x3800
	s_waitcnt lgkmcnt(13)
	v_mfma_f32_32x32x16_bf16 v[82:97], v[98:101], v[122:125], v[82:97]
	v_add_f32_e32 v255, v201, v255
	s_add_i32 s46, s12, 3
	v_add_f32_e32 v255, v202, v255
	s_cmpk_lt_u32 s12, 0x7d
	v_add_f32_e32 v255, v203, v255
	s_cselect_b64 s[42:43], -1, 0
	v_add_f32_e32 v255, v204, v255
	s_and_b64 s[44:45], s[42:43], exec
	s_cselect_b32 s44, 0, 0xffffff80
	s_waitcnt lgkmcnt(12)
	v_mfma_f32_32x32x16_bf16 v[66:81], v[102:105], v[122:125], v[66:81]
	v_add_f32_e32 v255, v205, v255
	s_add_i32 s58, s46, s44
	v_add_f32_e32 v255, v206, v255
	s_and_b64 s[42:43], s[42:43], exec
	v_add_f32_e32 v255, v207, v255
	s_cselect_b32 s43, s9, s30
	v_add_f32_e32 v255, v210, v255
	s_cselect_b32 s42, s8, s26
	v_add_f32_e32 v255, v211, v255
	s_lshl_b64 s[44:45], s[58:59], 17
	s_waitcnt lgkmcnt(11)
	v_mfma_f32_32x32x16_bf16 v[82:97], v[106:109], v[118:121], v[82:97]
	v_add_f32_e32 v255, v212, v255
	s_lshl_b64 s[42:43], s[42:43], 11
	v_add_f32_e32 v255, v213, v255
	s_add_u32 s44, s44, s42
	v_add_f32_e32 v255, v214, v255
	s_addc_u32 s45, s45, s43
	v_add_f32_e32 v255, v215, v255
	s_add_u32 s42, s20, s44
	s_addc_u32 s43, s21, s45
	s_waitcnt lgkmcnt(10)
	v_mfma_f32_32x32x16_bf16 v[66:81], v[110:113], v[118:121], v[66:81]
	v_add_f32_e32 v255, v149, v255
	s_add_u32 s44, s22, s44
	v_add_f32_e32 v255, v150, v255
	s_mul_i32 s47, s46, 0xab
	v_add_f32_e32 v255, v151, v255
	s_addc_u32 s45, s23, s45
	v_add_f32_e32 v255, v186, v255
	s_bfe_u32 s47, s47, 0x70009
	v_add_f32_e32 v255, v187, v255
	s_mul_i32 s47, s47, 3
	s_waitcnt lgkmcnt(9)
	v_mfma_f32_32x32x16_bf16 v[82:97], v[134:137], v[114:117], v[82:97]
	v_add_f32_e32 v255, v188, v255
	s_sub_i32 s46, s46, s47
	v_add_f32_e32 v255, v189, v255
	s_and_b32 s46, s46, 0xff
	v_add_f32_e32 v255, v208, v255
	s_lshl_b32 s46, s46, 14
	s_mov_b32 s101, s46
	v_add_f32_e32 v255, v209, v255
	s_add_i32 s46, s46, s27
	v_add_f32_e32 v99, v148, v255
	s_and_b32 s47, s36, 0xc000
	s_add_i32 s47, s47, s31
	s_cmpk_gt_u32 s12, 0x80
	s_cselect_b64 s[10:11], -1, 0
	s_and_b64 vcc, exec, s[10:11]
	s_cbranch_vccnz .LBB0_776
	v_lshl_add_u64 v[246:247], s[42:43], 0, v[146:147]
	s_mov_b32 m0, s46
	s_nop 0
	global_load_lds_dwordx4 v[246:247], off sc1
	v_lshl_add_u64 v[246:247], s[44:45], 0, v[142:143]
	s_mov_b32 m0, s47
	s_nop 0
	global_load_lds_dwordx4 v[246:247], off sc1
	v_lshl_add_u64 v[246:247], s[42:43], 0, v[144:145]
	s_add_i32 m0, s46, 0x2000
	s_nop 0
	global_load_lds_dwordx4 v[246:247], off sc1
	v_lshl_add_u64 v[246:247], s[44:45], 0, v[154:155]
	s_add_i32 m0, s47, 0x2000
	s_nop 0
	global_load_lds_dwordx4 v[246:247], off sc1
